# attention step B: the four remaining v_pk_add_f32 of the exp region as plain v_add_f32 pairs
# speedup vs baseline: 1.0035x; 1.0035x over previous
.LBB0_1009:
	v_mfma_f32_32x32x16_bf16 v[36:51], v[246:249], v[250:253], 0
	v_mfma_f32_32x32x16_bf16 v[52:67], v[144:147], v[100:103], v[36:51]
	v_mfma_f32_32x32x16_bf16 v[36:51], v[136:139], v[100:103], v[36:51]
	v_add_u32_e32 v255, s43, v200
	ds_read_b128 v[212:215], v181 offset:96
	ds_read_b128 v[216:219], v181 offset:128
	ds_read_b128 v[220:223], v181 offset:6752
	ds_read_b128 v[224:227], v181 offset:160
	ds_read_b128 v[228:231], v181 offset:6784
	ds_read_b128 v[238:241], v181 offset:6816
	ds_read_b128 v[160:163], v255 offset:53248
	ds_read_b128 v[164:167], v255 offset:53280
	ds_read_b128 v[184:187], v255 offset:57856
	ds_read_b128 v[180:183], v255 offset:57888
	ds_read_b128 v[156:159], v255 offset:53312
	ds_read_b128 v[152:155], v255 offset:53344
	v_add_u32_e32 v209, s41, v189
	v_mfma_f32_32x32x16_bf16 v[36:51], v[148:151], v[104:107], v[36:51]
	ds_read_b128 v[176:179], v255 offset:57920
	ds_read_b128 v[148:151], v255 offset:57952
	v_exp_f32_e32 v211, v84
	v_exp_f32_e32 v232, v68
	v_exp_f32_e32 v233, v85
	v_exp_f32_e32 v235, v69
	v_add_f32_e32 v68, v211, v232
	v_add_f32_e32 v69, v233, v235
	v_add_f32_e32 v68, v69, v68
	v_mfma_f32_32x32x16_bf16 v[52:67], v[172:175], v[104:107], v[52:67]
	v_exp_f32_e32 v173, v70
	v_exp_f32_e32 v172, v86
	v_exp_f32_e32 v174, v87
	v_exp_f32_e32 v175, v71
	v_add_f32_e32 v69, v172, v173
	v_add_f32_e32 v68, v69, v68
	v_mfma_f32_32x32x16_bf16 v[52:67], v[168:171], v[108:111], v[52:67]
	v_add_f32_e32 v69, v174, v175
	v_add_f32_e32 v168, v69, v68
	v_exp_f32_e32 v71, v88
	v_exp_f32_e32 v85, v72
	v_exp_f32_e32 v70, v89
	v_exp_f32_e32 v84, v73
	v_exp_f32_e32 v73, v90
	v_exp_f32_e32 v87, v74
	v_exp_f32_e32 v72, v91
	v_exp_f32_e32 v86, v75
	v_add_f32_e32 v68, v70, v84
	v_add_f32_e32 v69, v71, v85
	v_mfma_f32_32x32x16_bf16 v[36:51], v[140:143], v[108:111], v[36:51]
	v_add_f32_e32 v69, v69, v168
	v_add_f32_e32 v74, v68, v69
	v_add_f32_e64 v68, v72, v86
	v_add_f32_e64 v69, v73, v87
	ds_read_b128 v[132:135], v209
	ds_read_b128 v[128:131], v209 offset:32
	ds_read_b128 v[136:139], v209 offset:6656
	ds_read_b128 v[124:127], v209 offset:64
	v_add_f32_e32 v69, v69, v74
	v_add_f32_e32 v168, v68, v69
	v_exp_f32_e32 v75, v92
	v_exp_f32_e32 v89, v76
	v_exp_f32_e32 v74, v93
	v_exp_f32_e32 v88, v77
	v_exp_f32_e32 v77, v94
	s_waitcnt lgkmcnt(12)
	v_mfma_f32_32x32x16_bf16 v[36:51], v[220:223], v[112:115], v[36:51]
	v_exp_f32_e32 v91, v78
	v_exp_f32_e32 v76, v95
	v_exp_f32_e32 v90, v79
	v_add_f32_e32 v68, v74, v88
	v_add_f32_e32 v69, v75, v89
	ds_read_b128 v[144:147], v209 offset:6688
	ds_read_b128 v[140:143], v209 offset:6720
	v_mfma_f32_32x32x16_bf16 v[52:67], v[212:215], v[112:115], v[52:67]
	v_add_f32_e32 v69, v69, v168
	v_add_f32_e32 v78, v68, v69
	v_add_f32_e64 v68, v76, v90
	v_add_f32_e64 v69, v77, v91
	v_add_f32_e32 v69, v69, v78
	v_add_f32_e32 v168, v68, v69
	v_mfma_f32_32x32x16_bf16 v[36:51], v[228:231], v[116:119], v[36:51]
	v_exp_f32_e32 v79, v96
	v_exp_f32_e32 v93, v80
	v_exp_f32_e32 v78, v97
	v_exp_f32_e32 v92, v81
	v_mfma_f32_32x32x16_bf16 v[52:67], v[216:219], v[116:119], v[52:67]
	v_exp_f32_e32 v95, v98
	v_exp_f32_e32 v97, v82
	v_exp_f32_e32 v94, v99
	v_mfma_f32_32x32x16_bf16 v[36:51], v[238:241], v[120:123], v[36:51]
	v_exp_f32_e32 v96, v83
	v_add_f32_e32 v68, v78, v92
	v_add_f32_e32 v69, v79, v93
	s_nop 0
	v_add_f32_e32 v69, v69, v168
	v_add_f32_e32 v80, v68, v69
	v_add_f32_e32 v68, v94, v96
	v_add_f32_e32 v69, v95, v97
	v_mfma_f32_32x32x16_bf16 v[52:67], v[224:227], v[120:123], v[52:67]
	v_add_f32_e32 v69, v69, v80
	v_add_f32_e32 v68, v68, v69
	v_add_f32_e32 v209, v2, v68
	v_cvt_pk_bf16_f32 v68, v211, v233
	v_cvt_pk_bf16_f32 v69, v172, v174
	v_cvt_pk_bf16_f32 v70, v71, v70
	v_cvt_pk_bf16_f32 v71, v73, v72
	v_cvt_pk_bf16_f32 v80, v75, v74
	v_cvt_pk_bf16_f32 v81, v77, v76
	s_waitcnt lgkmcnt(11)
	v_mfma_f32_32x32x16_bf16 v[4:19], v[68:71], v[184:187], v[4:19]
	v_cvt_pk_bf16_f32 v82, v79, v78
	v_cvt_pk_bf16_f32 v83, v95, v94
	v_cvt_pk_bf16_f32 v76, v232, v235
	v_cvt_pk_bf16_f32 v77, v173, v175
	v_cvt_pk_bf16_f32 v78, v85, v84
	v_cvt_pk_bf16_f32 v79, v87, v86
	v_mfma_f32_32x32x16_bf16 v[20:35], v[68:71], v[160:163], v[20:35]
	v_cvt_pk_bf16_f32 v72, v89, v88
	v_cvt_pk_bf16_f32 v73, v91, v90
	v_cvt_pk_bf16_f32 v74, v93, v92
	v_cvt_pk_bf16_f32 v75, v97, v96
	s_cmp_ge_u32 s42, s36
	s_cbranch_scc1 .Lattn_exit
	s_mov_b32 s14, s41
	s_mov_b32 s15, s38
	s_mov_b32 s41, s45
	s_mov_b32 s38, s44
	s_mov_b32 s44, s40
	s_mov_b32 s40, s43
	s_mov_b32 s46, s42
	s_add_i32 s42, s46, 4
	s_min_u32 s43, s42, s37
	s_add_i32 s42, s46, 2
	s_min_u32 s45, s42, s37
	s_mulk_i32 s43, 0x3000
	s_add_u32 s48, s10, s43
	s_addc_u32 s49, s11, 0
	s_lshl_b32 s43, s45, 13
	s_add_u32 s50, s12, s43
	s_addc_u32 s51, s13, 0
	s_add_i32 m0, s22, s38
	s_and_b64 s[52:53], s[4:5], exec
	s_waitcnt vmcnt(3) lgkmcnt(0)
	s_barrier
	s_branch .LBB0_999
